# static s_setprio 1 for waves 4-7 during the LRU item loops (both passes); on top of v24
# baseline (speedup 1.0000x reference)
; template <int PASS> __device__ __forceinline__ void lru_pass(LAS unsigned char* lds, const MixP& p, const Args& a, int cv_layer, bf16_t* cv_slot, unsigned* cv_counter) {
;     ...
;         {
;             const int NI = 8 * NCH, jlo = (int)((long)wi * NI / nw), jhi = (int)((long)(wi + 1) * NI / nw); float Hrun[8];
;             for (int j = jlo; j < jhi; ++j) lru_wave_item<PASS>(lds, vw, j / NCH, j % NCH, h, p, lane, Hrun, j > jlo && (j % NCH) != 0);
.LBB0_664:
	s_cmp_ge_i32 s10, s12
	s_cbranch_scc1 .LBB0_671
	v_readfirstlane_b32 s100, v252
	s_nop 3
	s_lshr_b32 s100, s100, 6
	s_cmp_ge_u32 s100, 4
	s_cbranch_scc0 .Llruprio_1
	s_setprio 1
.Llruprio_1:
	v_mov_b32_e32 v153, s29
	v_or_b32_e32 v152, s28, v134
	v_lshl_add_u64 v[154:155], s[28:29], 1, v[148:149]
	s_branch .LBB0_667

; #define LAS __attribute__((address_space(3)))
; template <int PASS> __device__ __forceinline__ void lru_pass(LAS unsigned char* lds, const MixP& p, const Args& a, int cv_layer, bf16_t* cv_slot, unsigned* cv_counter) {
;     ...
;             for (int j = jlo; j < jhi; ++j) lru_wave_item<PASS>(lds, vw, j / NCH, j % NCH, h, p, lane, Hrun, j > jlo && (j % NCH) != 0);
;         }
;         if (PASS == 1 && first) {
;             pool_items(lds, vw, bid & 3, (bid >> 2) * 8 + wave, ((G - (bid & 3) + 3) >> 2) * 8, p, lane);
;             if (cv_layer >= 0) convert_dynamic(a, cv_layer, cv_slot, (LAS float*)vw, cv_counter, lane);
; __device__ __forceinline__ void pool_items(LAS unsigned char* lds, LAS unsigned char* vw, int g, int wi, int nw, const MixP& p, int lane) {
;     const int fr = lane & 15, fq = lane >> 4, cg = fr;
;     float pb[8], ps[8];
; #pragma unroll
;     for (int n = 0; n < 8; ++n) { pb[n] = p.pool_b[g * 128 + 16 * n + fr]; ps[n] = p.pool_scale[g * 128 + 16 * n + fr]; }
.LBB0_671:
	s_setprio 0
	s_and_b64 vcc, exec, s[8:9]
	s_cbranch_vccz .LBB0_649
	v_readlane_b32 s2, v255, 10
	v_readlane_b32 s3, v255, 11
	s_andn2_b64 vcc, exec, s[2:3]
	s_cbranch_vccnz .LBB0_688
	global_load_dword v62, v[130:131], off
	global_load_dword v63, v[130:131], off offset:64
	global_load_dword v64, v[130:131], off offset:128
	global_load_dword v65, v[130:131], off offset:192
	global_load_dword v66, v[130:131], off offset:256
	global_load_dword v67, v[130:131], off offset:320
	global_load_dword v68, v[130:131], off offset:384
	global_load_dword v69, v[130:131], off offset:448
	global_load_dword v70, v[132:133], off
	global_load_dword v71, v[132:133], off offset:64
	global_load_dword v72, v[132:133], off offset:128
	global_load_dword v73, v[132:133], off offset:192
	global_load_dword v74, v[132:133], off offset:256
	global_load_dword v75, v[132:133], off offset:320
	global_load_dword v76, v[132:133], off offset:384
	global_load_dword v77, v[132:133], off offset:448
	s_mov_b32 s19, s69
	s_branch .LBB0_675

; template <int PASS> __device__ __forceinline__ void lru_pass(LAS unsigned char* lds, const MixP& p, const Args& a, int cv_layer, bf16_t* cv_slot, unsigned* cv_counter) {
;     ...
;         first = false;
;         __syncthreads();
;     }
.LBB0_797:
	s_setprio 0
	v_readlane_b32 s0, v254, 2
	s_add_i32 s17, s17, s0
	s_cmp_gt_i32 s17, 9
	s_barrier
	s_cbranch_scc1 .LBB0_822

; template <int PASS> __device__ __forceinline__ void lru_pass(LAS unsigned char* lds, const MixP& p, const Args& a, int cv_layer, bf16_t* cv_slot, unsigned* cv_counter) {
;     ...
;             const int NI = 8 * NCH, jlo = (int)((long)wi * NI / nw), jhi = (int)((long)(wi + 1) * NI / nw); float Hrun[8];
;             for (int j = jlo; j < jhi; ++j) lru_wave_item<PASS>(lds, vw, j / NCH, j % NCH, h, p, lane, Hrun, j > jlo && (j % NCH) != 0);
.LBB0_809:
	s_cmp_ge_i32 s0, s10
	s_cbranch_scc1 .LBB0_797
	v_readfirstlane_b32 s100, v252
	s_nop 3
	s_lshr_b32 s100, s100, 6
	s_cmp_ge_u32 s100, 4
	s_cbranch_scc0 .Llruprio_2
	s_setprio 1
.Llruprio_2:
	v_mov_b32_e32 v151, s13
	v_or_b32_e32 v150, s12, v142
	s_lshl_b64 s[12:13], s[12:13], 1
	v_lshl_add_u64 v[152:153], v[144:145], 0, s[12:13]
	v_lshl_add_u64 v[154:155], v[146:147], 0, s[12:13]
	v_lshl_add_u64 v[156:157], v[148:149], 0, s[12:13]
	s_mov_b32 s1, s0
